# FFN seams (out-proj->up-proj, up-proj->fix-up->down-proj) become 4-workgroup panel counters without L2 write-back (XCC co-location checked at run time, fallback write-back); fix-up pass remapped panel
# speedup vs baseline: 1.3289x; 1.0151x over previous
_Z6mk_fwd4Args:
	s_load_dwordx2 s[48:49], s[0:1], 0x70
	s_load_dwordx4 s[28:31], s[0:1], 0x60
	s_load_dwordx8 s[36:43], s[0:1], 0x40
	v_writelane_b32 v233, s0, 0
	s_load_dwordx4 s[4:7], s[0:1], 0x78
	v_and_b32_e32 v188, 0x3ff, v0
	v_writelane_b32 v233, s1, 1
	v_readfirstlane_b32 s33, v188
	v_cmp_gt_u32_e32 vcc, 2, v188
	s_waitcnt lgkmcnt(0)
	v_writelane_b32 v233, s4, 2
	s_nop 1
	v_writelane_b32 v233, s5, 3
	v_writelane_b32 v233, s6, 4
	v_writelane_b32 v233, s7, 5
	s_and_saveexec_b64 s[4:5], vcc
	v_lshl_add_u32 v1, v188, 2, 0
	v_add_u32_e32 v1, 0x25fc0, v1
	v_mov_b32_e32 v2, 0
	ds_write_b32 v1, v2
	s_or_b64 exec, exec, s[4:5]
	s_add_u32 s0, s48, 0x4000
	s_addc_u32 s1, s49, 0
	s_waitcnt lgkmcnt(0)
	s_barrier
	v_writelane_b32 v233, s0, 6
	s_getreg_b32 s3, hwreg(HW_REG_XCC_ID, 0, 4)
	s_nop 0
	v_writelane_b32 v233, s1, 7
	s_and_b32 s0, s3, 15
	v_writelane_b32 v233, s0, 8
	v_cmp_eq_u32_e64 s[0:1], 0, v188
	s_nop 1
	v_writelane_b32 v233, s0, 9
	s_nop 1
	v_writelane_b32 v233, s1, 10
	s_and_saveexec_b64 s[6:7], s[0:1]
	s_cbranch_execz .LBB0_5
	s_mov_b64 s[8:9], exec
	v_mbcnt_lo_u32_b32 v1, s8, 0
	v_mbcnt_hi_u32_b32 v1, s9, v1
	v_cmp_eq_u32_e32 vcc, 0, v1
	s_and_b64 s[4:5], exec, vcc
	s_mov_b64 exec, s[4:5]
	s_cbranch_execz .LBB0_5
	v_readlane_b32 s0, v233, 8
	s_lshl_b32 s3, s0, 8
	s_bcnt1_i32_b64 s4, s[8:9]
	v_readlane_b32 s0, v233, 6
	v_mov_b32_e32 v1, s3
	v_mov_b32_e32 v2, s4
	v_readlane_b32 s1, v233, 7
	s_nop 4
	global_atomic_add v1, v2, s[0:1] offset:1024
	s_and_b32 s3, s2, 7
	s_lshl_b32 s3, s3, 6
	s_add_i32 s3, s3, 0x8000
	v_readlane_b32 s4, v233, 8
	v_mov_b32_e32 v3, s3
	s_lshl_b32 s4, 1, s4
	v_mov_b32_e32 v4, s4
	global_atomic_or v3, v4, s[48:49]

.Lxb0_done:
	s_and_b32 s3, s2, 7
	s_lshl_b32 s3, s3, 6
	s_add_i32 s3, s3, 0x8000
	v_mov_b32_e32 v0, s3
	global_load_dword v2, v0, s[48:49] sc1
	s_waitcnt vmcnt(0)
	v_readfirstlane_b32 s4, v2
	s_nop 3
	s_bcnt1_i32_b32 s4, s4
	s_cmp_eq_u32 s4, 1
	s_cselect_b32 s4, 1, 0
	s_nop 0
	v_writelane_b32 v233, s4, 60

.LBB0_850:
	v_readlane_b32 s4, v233, 2
	v_readlane_b32 s5, v233, 3
	v_readlane_b32 s6, v233, 4
	v_readlane_b32 s7, v233, 5
	s_cmp_gt_i32 s5, 5
	s_cselect_b64 s[6:7], -1, 0
	s_and_b64 s[4:5], s[16:17], s[6:7]
	s_andn2_b64 vcc, exec, s[4:5]
	s_cbranch_vccnz .LBB0_904
	s_waitcnt vmcnt(0)
	v_readlane_b32 s0, v233, 9
	v_readlane_b32 s1, v233, 10
	s_waitcnt vmcnt(0) lgkmcnt(0)
	s_barrier
	s_and_saveexec_b64 s[8:9], s[0:1]
	s_cbranch_execz .LBB0_903
	s_and_b32 s3, s2, 7
	s_lshr_b32 s1, s2, 3
	s_and_b32 s1, s1, 7
	s_lshl_b32 s3, s3, 3
	s_add_i32 s3, s3, s1
	s_lshl_b32 s3, s3, 6
	s_add_i32 s3, s3, 0x9000
	v_mov_b32_e32 v0, s3
	s_cmp_eq_u32 s1, 0
	s_cselect_b32 s0, 0, 64
	s_sub_i32 s3, s3, s0
	v_mov_b32_e32 v5, s3
	v_mov_b32_e32 v1, 1
	v_readlane_b32 s4, v233, 60
	s_waitcnt vmcnt(0) lgkmcnt(0)
	s_cmp_eq_u32 s4, 1
	s_cbranch_scc1 .Lpa_colo
	buffer_wbl2 sc1
	s_waitcnt vmcnt(0)
.Lpa_colo:
	global_atomic_add v0, v1, s[48:49]
	buffer_inv sc1
	s_mov_b32 s5, 0
.Lpa_spin:
	global_load_dword v4, v0, s[48:49] sc1
	s_waitcnt vmcnt(0)
	v_readfirstlane_b32 s4, v4
	s_add_u32 s5, s5, 1
	s_nop 3
	s_cmp_ge_u32 s4, 4
	s_cbranch_scc1 .Lpa_done
	s_sleep 1
	s_cmp_lt_u32 s5, 0x40000
	s_cbranch_scc1 .Lpa_spin

.LBB0_943:
	v_readlane_b32 s4, v233, 2
	v_readlane_b32 s5, v233, 3
	v_readlane_b32 s6, v233, 4
	v_readlane_b32 s7, v233, 5
	s_cmp_gt_i32 s5, 6
	s_cselect_b64 s[6:7], -1, 0
	s_and_b64 s[4:5], s[26:27], s[6:7]
	s_andn2_b64 vcc, exec, s[4:5]
	s_cbranch_vccnz .LBB0_997
	s_waitcnt vmcnt(0)
	v_readlane_b32 s0, v233, 9
	v_readlane_b32 s1, v233, 10
	s_waitcnt vmcnt(0) lgkmcnt(0)
	s_barrier
	s_and_saveexec_b64 s[8:9], s[0:1]
	s_cbranch_execz .LBB0_996
	s_and_b32 s3, s2, 7
	s_lshr_b32 s1, s2, 3
	s_and_b32 s1, s1, 7
	s_lshl_b32 s3, s3, 3
	s_add_i32 s3, s3, s1
	s_lshl_b32 s3, s3, 6
	s_add_i32 s3, s3, 0xa000
	v_mov_b32_e32 v0, s3
	s_cmp_eq_u32 s1, 0
	s_cselect_b32 s0, 0, 64
	s_sub_i32 s3, s3, s0
	v_mov_b32_e32 v5, s3
	v_mov_b32_e32 v1, 1
	v_readlane_b32 s4, v233, 60
	s_waitcnt vmcnt(0) lgkmcnt(0)
	s_cmp_eq_u32 s4, 1
	s_cbranch_scc1 .Lpb_colo
	buffer_wbl2 sc1
	s_waitcnt vmcnt(0)

.Lpb_spin:
	global_load_dword v4, v0, s[48:49] sc1
	global_load_dword v3, v5, s[48:49] sc1
	s_waitcnt vmcnt(0)
	v_readfirstlane_b32 s4, v4
	v_readfirstlane_b32 s16, v3
	s_add_u32 s5, s5, 1
	s_nop 3
	s_min_u32 s4, s4, s16
	s_cmp_ge_u32 s4, 4
	s_cbranch_scc1 .Lpb_done
	s_sleep 1
	s_cmp_lt_u32 s5, 0x40000
	s_cbranch_scc1 .Lpb_spin

.LBB0_997:
	v_readlane_b32 s8, v233, 2
	s_cmp_lt_i32 s8, 7
	v_readlane_b32 s9, v233, 3
	s_cselect_b64 s[4:5], -1, 0
	s_and_b64 s[8:9], s[4:5], s[6:7]
	s_andn2_b64 vcc, exec, s[8:9]
	v_readlane_b32 s10, v233, 4
	v_readlane_b32 s11, v233, 5
	s_cbranch_vccnz .LBB0_1008
	s_and_b32 s0, s2, 7
	s_lshr_b32 s1, s2, 3
	s_and_b32 s4, s1, 7
	s_lshr_b32 s1, s1, 3
	s_lshl_b32 s0, s0, 3
	s_add_i32 s0, s0, s4
	s_mul_i32 s0, s0, 0x1600
	s_mul_i32 s1, s1, 0x580
	s_add_i32 s0, s0, s1
	v_add_u32_e32 v219, s0, v188
	s_add_i32 s5, s0, 0x57f
	v_cmp_ge_i32_e32 vcc, s5, v219
	s_and_saveexec_b64 s[6:7], vcc
	s_cbranch_execz .LBB0_1007
	s_add_u32 s10, s48, 0xec00000
	s_addc_u32 s11, s49, 0
	s_add_u32 s12, s48, 0xf000000
	s_addc_u32 s13, s49, 0
	v_readlane_b32 s0, v233, 0
	v_readlane_b32 s1, v233, 1
	s_add_u32 s14, s0, 0x88
	s_addc_u32 s15, s1, 0
	s_mov_b64 s[16:17], 0
	s_waitcnt lgkmcnt(0)
	s_mov_b32 s3, 0x2e8ba2e9
	s_waitcnt vmcnt(0)
	v_mov_b32_e32 v1, 0
	s_movk_i32 s4, 0x1600
	s_branch .LBB0_1002

.LBB0_1001:
	s_or_b64 exec, exec, s[18:19]
	v_add_u32_e32 v219, 0x200, v219
	v_cmp_lt_i32_e32 vcc, s5, v219
	s_or_b64 s[16:17], vcc, s[16:17]
	s_andn2_b64 exec, exec, s[16:17]
	s_cbranch_execz .LBB0_1007

.LBB0_1008:
	v_readlane_b32 s4, v233, 2
	v_readlane_b32 s5, v233, 3
	v_readlane_b32 s6, v233, 4
	v_readlane_b32 s7, v233, 5
	s_cmp_gt_i32 s5, 7
	s_cselect_b64 s[6:7], -1, 0
	s_and_b64 s[4:5], s[8:9], s[6:7]
	s_andn2_b64 vcc, exec, s[4:5]
	s_cbranch_vccnz .LBB0_1062
	s_waitcnt vmcnt(0)
	v_readlane_b32 s0, v233, 9
	v_readlane_b32 s1, v233, 10
	s_waitcnt vmcnt(0) lgkmcnt(0)
	s_barrier
	s_and_saveexec_b64 s[8:9], s[0:1]
	s_cbranch_execz .LBB0_1061
	s_and_b32 s3, s2, 7
	s_lshr_b32 s1, s2, 3
	s_and_b32 s1, s1, 7
	s_lshl_b32 s3, s3, 3
	s_add_i32 s3, s3, s1
	s_lshl_b32 s3, s3, 6
	s_add_i32 s3, s3, 0xb000
	v_mov_b32_e32 v0, s3
	s_cmp_eq_u32 s1, 0
	s_cselect_b32 s0, 0, 64
	s_sub_i32 s3, s3, s0
	v_mov_b32_e32 v5, s3
	v_mov_b32_e32 v1, 1
	v_readlane_b32 s4, v233, 60
	s_waitcnt vmcnt(0) lgkmcnt(0)
	s_cmp_eq_u32 s4, 1
	s_cbranch_scc1 .Lpc_colo
	buffer_wbl2 sc1
	s_waitcnt vmcnt(0)
